# combo10 + S5 scan: complex rotation done with one pk_fma (neg_lo only) instead of two pk_fma + v_mov (bit-identical)
# baseline (speedup 1.0000x reference)
.LBB0_208:
	s_add_i32 s12, s10, s11
	v_mov_b32_e32 v17, s12
	ds_read_b128 v[26:29], v17
	ds_read_b128 v[30:33], v17 offset:16
	ds_read_b128 v[38:41], v17 offset:32
	ds_read_b128 v[92:95], v17 offset:48
	s_addk_i32 s11, 0x200
	s_waitcnt lgkmcnt(0)
	v_pk_fma_f32 v[18:19], v[26:27], v[82:83], 0 op_sel_hi:[0,1,0]
	s_waitcnt lgkmcnt(2)
	v_pk_fma_f32 v[22:23], v[30:31], v[64:65], 0 op_sel_hi:[0,1,0]
	s_waitcnt lgkmcnt(1)
	v_pk_fma_f32 v[18:19], v[38:39], v[56:57], v[18:19] op_sel_hi:[0,1,1]
	s_waitcnt lgkmcnt(0)
	v_pk_fma_f32 v[22:23], v[92:93], v[48:49], v[22:23] op_sel_hi:[0,1,1]
	v_pk_fma_f32 v[18:19], v[26:27], v[62:63], v[18:19] op_sel:[1,0,0]
	v_pk_fma_f32 v[22:23], v[30:31], v[50:51], v[22:23] op_sel:[1,0,0]
	v_pk_fma_f32 v[18:19], v[38:39], v[42:43], v[18:19] op_sel:[1,0,0]
	v_pk_fma_f32 v[22:23], v[92:93], v[34:35], v[22:23] op_sel:[1,0,0]
	v_pk_fma_f32 v[18:19], v[28:29], v[58:59], v[18:19] op_sel_hi:[0,1,1]
	v_pk_fma_f32 v[22:23], v[32:33], v[54:55], v[22:23] op_sel_hi:[0,1,1]
	v_pk_fma_f32 v[18:19], v[40:41], v[46:47], v[18:19] op_sel_hi:[0,1,1]
	v_pk_fma_f32 v[22:23], v[94:95], v[84:85], v[22:23] op_sel_hi:[0,1,1]
	v_pk_fma_f32 v[18:19], v[28:29], v[60:61], v[18:19] op_sel:[1,0,0]
	v_pk_fma_f32 v[22:23], v[32:33], v[52:53], v[22:23] op_sel:[1,0,0]
	v_pk_fma_f32 v[18:19], v[40:41], v[44:45], v[18:19] op_sel:[1,0,0]
	v_pk_fma_f32 v[22:23], v[94:95], v[36:37], v[22:23] op_sel:[1,0,0]
	v_pk_mul_f32 v[26:27], v[80:81], v[76:77] op_sel:[0,1] op_sel_hi:[1,0]
	v_pk_add_f32 v[18:19], v[18:19], v[22:23]
	v_pk_fma_f32 v[22:23], v[78:79], v[76:77], v[26:27] neg_lo:[0,0,1]
	s_cmpk_eq_i32 s11, 0x400
	v_pk_add_f32 v[18:19], v[22:23], v[18:19]
	s_nop 0
	v_cvt_pk_bf16_f32 v22, v18, s0
	ds_write_b16 v16, v22
	v_cvt_pk_bf16_f32 v22, v19, s0
	ds_write_b16 v16, v22 offset:128
	ds_read_b128 v[26:29], v17 offset:64
	ds_read_b128 v[30:33], v17 offset:80
	ds_read_b128 v[38:41], v17 offset:96
	ds_read_b128 v[92:95], v17 offset:112
	s_waitcnt lgkmcnt(0)
	v_pk_fma_f32 v[22:23], v[26:27], v[82:83], 0 op_sel_hi:[0,1,0]
	s_waitcnt lgkmcnt(2)
	v_pk_fma_f32 v[76:77], v[30:31], v[64:65], 0 op_sel_hi:[0,1,0]
	s_waitcnt lgkmcnt(1)
	v_pk_fma_f32 v[22:23], v[38:39], v[56:57], v[22:23] op_sel_hi:[0,1,1]
	s_waitcnt lgkmcnt(0)
	v_pk_fma_f32 v[76:77], v[92:93], v[48:49], v[76:77] op_sel_hi:[0,1,1]
	v_pk_fma_f32 v[22:23], v[26:27], v[62:63], v[22:23] op_sel:[1,0,0]
	v_pk_fma_f32 v[26:27], v[30:31], v[50:51], v[76:77] op_sel:[1,0,0]
	v_pk_fma_f32 v[22:23], v[38:39], v[42:43], v[22:23] op_sel:[1,0,0]
	v_pk_fma_f32 v[26:27], v[92:93], v[34:35], v[26:27] op_sel:[1,0,0]
	v_pk_fma_f32 v[22:23], v[28:29], v[58:59], v[22:23] op_sel_hi:[0,1,1]
	v_pk_fma_f32 v[26:27], v[32:33], v[54:55], v[26:27] op_sel_hi:[0,1,1]
	v_pk_fma_f32 v[22:23], v[40:41], v[46:47], v[22:23] op_sel_hi:[0,1,1]
	v_pk_fma_f32 v[26:27], v[94:95], v[84:85], v[26:27] op_sel_hi:[0,1,1]
	v_pk_fma_f32 v[22:23], v[28:29], v[60:61], v[22:23] op_sel:[1,0,0]
	v_pk_fma_f32 v[26:27], v[32:33], v[52:53], v[26:27] op_sel:[1,0,0]
	v_pk_fma_f32 v[22:23], v[40:41], v[44:45], v[22:23] op_sel:[1,0,0]
	v_pk_fma_f32 v[26:27], v[94:95], v[36:37], v[26:27] op_sel:[1,0,0]
	v_pk_mul_f32 v[28:29], v[80:81], v[18:19] op_sel:[0,1] op_sel_hi:[1,0]
	v_pk_add_f32 v[22:23], v[22:23], v[26:27]
	v_pk_fma_f32 v[26:27], v[78:79], v[18:19], v[28:29] neg_lo:[0,0,1]
	s_nop 0
	v_pk_add_f32 v[18:19], v[26:27], v[22:23]
	s_nop 0
	v_cvt_pk_bf16_f32 v22, v18, s0
	ds_write_b16 v16, v22 offset:272
	v_cvt_pk_bf16_f32 v22, v19, s0
	ds_write_b16 v16, v22 offset:400
	ds_read_b128 v[26:29], v17 offset:128
	ds_read_b128 v[30:33], v17 offset:144
	ds_read_b128 v[38:41], v17 offset:160
	ds_read_b128 v[92:95], v17 offset:176
	s_waitcnt lgkmcnt(0)
	v_pk_fma_f32 v[22:23], v[26:27], v[82:83], 0 op_sel_hi:[0,1,0]
	s_waitcnt lgkmcnt(2)
	v_pk_fma_f32 v[76:77], v[30:31], v[64:65], 0 op_sel_hi:[0,1,0]
	s_waitcnt lgkmcnt(1)
	v_pk_fma_f32 v[22:23], v[38:39], v[56:57], v[22:23] op_sel_hi:[0,1,1]
	s_waitcnt lgkmcnt(0)
	v_pk_fma_f32 v[76:77], v[92:93], v[48:49], v[76:77] op_sel_hi:[0,1,1]
	v_pk_fma_f32 v[22:23], v[26:27], v[62:63], v[22:23] op_sel:[1,0,0]
	v_pk_fma_f32 v[26:27], v[30:31], v[50:51], v[76:77] op_sel:[1,0,0]
	v_pk_fma_f32 v[22:23], v[38:39], v[42:43], v[22:23] op_sel:[1,0,0]
	v_pk_fma_f32 v[26:27], v[92:93], v[34:35], v[26:27] op_sel:[1,0,0]
	v_pk_fma_f32 v[22:23], v[28:29], v[58:59], v[22:23] op_sel_hi:[0,1,1]
	v_pk_fma_f32 v[26:27], v[32:33], v[54:55], v[26:27] op_sel_hi:[0,1,1]
	v_pk_fma_f32 v[22:23], v[40:41], v[46:47], v[22:23] op_sel_hi:[0,1,1]
	v_pk_fma_f32 v[26:27], v[94:95], v[84:85], v[26:27] op_sel_hi:[0,1,1]
	v_pk_fma_f32 v[22:23], v[28:29], v[60:61], v[22:23] op_sel:[1,0,0]
	v_pk_fma_f32 v[26:27], v[32:33], v[52:53], v[26:27] op_sel:[1,0,0]
	v_pk_fma_f32 v[22:23], v[40:41], v[44:45], v[22:23] op_sel:[1,0,0]
	v_pk_fma_f32 v[26:27], v[94:95], v[36:37], v[26:27] op_sel:[1,0,0]
	v_pk_mul_f32 v[28:29], v[80:81], v[18:19] op_sel:[0,1] op_sel_hi:[1,0]
	v_pk_add_f32 v[22:23], v[22:23], v[26:27]
	v_pk_fma_f32 v[26:27], v[78:79], v[18:19], v[28:29] neg_lo:[0,0,1]
	s_nop 0
	v_pk_add_f32 v[18:19], v[26:27], v[22:23]
	s_nop 0
	v_cvt_pk_bf16_f32 v22, v18, s0
	ds_write_b16 v16, v22 offset:544
	v_cvt_pk_bf16_f32 v22, v19, s0
	ds_write_b16 v16, v22 offset:672
	ds_read_b128 v[26:29], v17 offset:192
	ds_read_b128 v[30:33], v17 offset:208
	ds_read_b128 v[38:41], v17 offset:224
	ds_read_b128 v[92:95], v17 offset:240
	s_waitcnt lgkmcnt(0)
	v_pk_fma_f32 v[22:23], v[26:27], v[82:83], 0 op_sel_hi:[0,1,0]
	s_waitcnt lgkmcnt(2)
	v_pk_fma_f32 v[76:77], v[30:31], v[64:65], 0 op_sel_hi:[0,1,0]
	s_waitcnt lgkmcnt(1)
	v_pk_fma_f32 v[22:23], v[38:39], v[56:57], v[22:23] op_sel_hi:[0,1,1]
	s_waitcnt lgkmcnt(0)
	v_pk_fma_f32 v[76:77], v[92:93], v[48:49], v[76:77] op_sel_hi:[0,1,1]
	v_pk_fma_f32 v[22:23], v[26:27], v[62:63], v[22:23] op_sel:[1,0,0]
	v_pk_fma_f32 v[26:27], v[30:31], v[50:51], v[76:77] op_sel:[1,0,0]
	v_pk_fma_f32 v[22:23], v[38:39], v[42:43], v[22:23] op_sel:[1,0,0]
	v_pk_fma_f32 v[26:27], v[92:93], v[34:35], v[26:27] op_sel:[1,0,0]
	v_pk_fma_f32 v[22:23], v[28:29], v[58:59], v[22:23] op_sel_hi:[0,1,1]
	v_pk_fma_f32 v[26:27], v[32:33], v[54:55], v[26:27] op_sel_hi:[0,1,1]
	v_pk_fma_f32 v[22:23], v[40:41], v[46:47], v[22:23] op_sel_hi:[0,1,1]
	v_pk_fma_f32 v[26:27], v[94:95], v[84:85], v[26:27] op_sel_hi:[0,1,1]
	v_pk_fma_f32 v[22:23], v[28:29], v[60:61], v[22:23] op_sel:[1,0,0]
	v_pk_fma_f32 v[26:27], v[32:33], v[52:53], v[26:27] op_sel:[1,0,0]
	v_pk_fma_f32 v[22:23], v[40:41], v[44:45], v[22:23] op_sel:[1,0,0]
	v_pk_fma_f32 v[26:27], v[94:95], v[36:37], v[26:27] op_sel:[1,0,0]
	v_pk_mul_f32 v[28:29], v[80:81], v[18:19] op_sel:[0,1] op_sel_hi:[1,0]
	v_pk_add_f32 v[22:23], v[22:23], v[26:27]
	v_pk_fma_f32 v[26:27], v[78:79], v[18:19], v[28:29] neg_lo:[0,0,1]
	s_nop 0
	v_pk_add_f32 v[18:19], v[26:27], v[22:23]
	s_nop 0
	v_cvt_pk_bf16_f32 v22, v18, s0
	ds_write_b16 v16, v22 offset:816
	v_cvt_pk_bf16_f32 v22, v19, s0
	ds_write_b16 v16, v22 offset:944
	ds_read_b128 v[26:29], v17 offset:256
	ds_read_b128 v[30:33], v17 offset:272
	ds_read_b128 v[38:41], v17 offset:288
	ds_read_b128 v[92:95], v17 offset:304
	s_waitcnt lgkmcnt(0)
	v_pk_fma_f32 v[22:23], v[26:27], v[82:83], 0 op_sel_hi:[0,1,0]
	s_waitcnt lgkmcnt(2)
	v_pk_fma_f32 v[76:77], v[30:31], v[64:65], 0 op_sel_hi:[0,1,0]
	s_waitcnt lgkmcnt(1)
	v_pk_fma_f32 v[22:23], v[38:39], v[56:57], v[22:23] op_sel_hi:[0,1,1]
	s_waitcnt lgkmcnt(0)
	v_pk_fma_f32 v[76:77], v[92:93], v[48:49], v[76:77] op_sel_hi:[0,1,1]
	v_pk_fma_f32 v[22:23], v[26:27], v[62:63], v[22:23] op_sel:[1,0,0]
	v_pk_fma_f32 v[26:27], v[30:31], v[50:51], v[76:77] op_sel:[1,0,0]
	v_pk_fma_f32 v[22:23], v[38:39], v[42:43], v[22:23] op_sel:[1,0,0]
	v_pk_fma_f32 v[26:27], v[92:93], v[34:35], v[26:27] op_sel:[1,0,0]
	v_pk_fma_f32 v[22:23], v[28:29], v[58:59], v[22:23] op_sel_hi:[0,1,1]
	v_pk_fma_f32 v[26:27], v[32:33], v[54:55], v[26:27] op_sel_hi:[0,1,1]
	v_pk_fma_f32 v[22:23], v[40:41], v[46:47], v[22:23] op_sel_hi:[0,1,1]
	v_pk_fma_f32 v[26:27], v[94:95], v[84:85], v[26:27] op_sel_hi:[0,1,1]
	v_pk_fma_f32 v[22:23], v[28:29], v[60:61], v[22:23] op_sel:[1,0,0]
	v_pk_fma_f32 v[26:27], v[32:33], v[52:53], v[26:27] op_sel:[1,0,0]
	v_pk_fma_f32 v[22:23], v[40:41], v[44:45], v[22:23] op_sel:[1,0,0]
	v_pk_fma_f32 v[26:27], v[94:95], v[36:37], v[26:27] op_sel:[1,0,0]
	v_pk_mul_f32 v[28:29], v[80:81], v[18:19] op_sel:[0,1] op_sel_hi:[1,0]
	v_pk_add_f32 v[22:23], v[22:23], v[26:27]
	v_pk_fma_f32 v[26:27], v[78:79], v[18:19], v[28:29] neg_lo:[0,0,1]
	s_nop 0
	v_pk_add_f32 v[18:19], v[26:27], v[22:23]
	s_nop 0
	v_cvt_pk_bf16_f32 v22, v18, s0
	ds_write_b16 v16, v22 offset:1088
	v_cvt_pk_bf16_f32 v22, v19, s0
	ds_write_b16 v16, v22 offset:1216
	ds_read_b128 v[26:29], v17 offset:320
	ds_read_b128 v[30:33], v17 offset:336
	ds_read_b128 v[38:41], v17 offset:352
	ds_read_b128 v[92:95], v17 offset:368
	s_waitcnt lgkmcnt(0)
	v_pk_fma_f32 v[22:23], v[26:27], v[82:83], 0 op_sel_hi:[0,1,0]
	s_waitcnt lgkmcnt(2)
	v_pk_fma_f32 v[76:77], v[30:31], v[64:65], 0 op_sel_hi:[0,1,0]
	s_waitcnt lgkmcnt(1)
	v_pk_fma_f32 v[22:23], v[38:39], v[56:57], v[22:23] op_sel_hi:[0,1,1]
	s_waitcnt lgkmcnt(0)
	v_pk_fma_f32 v[76:77], v[92:93], v[48:49], v[76:77] op_sel_hi:[0,1,1]
	v_pk_fma_f32 v[22:23], v[26:27], v[62:63], v[22:23] op_sel:[1,0,0]
	v_pk_fma_f32 v[26:27], v[30:31], v[50:51], v[76:77] op_sel:[1,0,0]
	v_pk_fma_f32 v[22:23], v[38:39], v[42:43], v[22:23] op_sel:[1,0,0]
	v_pk_fma_f32 v[26:27], v[92:93], v[34:35], v[26:27] op_sel:[1,0,0]
	v_pk_fma_f32 v[22:23], v[28:29], v[58:59], v[22:23] op_sel_hi:[0,1,1]
	v_pk_fma_f32 v[26:27], v[32:33], v[54:55], v[26:27] op_sel_hi:[0,1,1]
	v_pk_fma_f32 v[22:23], v[40:41], v[46:47], v[22:23] op_sel_hi:[0,1,1]
	v_pk_fma_f32 v[26:27], v[94:95], v[84:85], v[26:27] op_sel_hi:[0,1,1]
	v_pk_fma_f32 v[22:23], v[28:29], v[60:61], v[22:23] op_sel:[1,0,0]
	v_pk_fma_f32 v[26:27], v[32:33], v[52:53], v[26:27] op_sel:[1,0,0]
	v_pk_fma_f32 v[22:23], v[40:41], v[44:45], v[22:23] op_sel:[1,0,0]
	v_pk_fma_f32 v[26:27], v[94:95], v[36:37], v[26:27] op_sel:[1,0,0]
	v_pk_mul_f32 v[28:29], v[80:81], v[18:19] op_sel:[0,1] op_sel_hi:[1,0]
	v_pk_add_f32 v[22:23], v[22:23], v[26:27]
	v_pk_fma_f32 v[26:27], v[78:79], v[18:19], v[28:29] neg_lo:[0,0,1]
	s_nop 0
	v_pk_add_f32 v[18:19], v[26:27], v[22:23]
	s_nop 0
	v_cvt_pk_bf16_f32 v22, v18, s0
	ds_write_b16 v16, v22 offset:1360
	v_cvt_pk_bf16_f32 v22, v19, s0
	ds_write_b16 v16, v22 offset:1488
	ds_read_b128 v[26:29], v17 offset:384
	ds_read_b128 v[30:33], v17 offset:400
	ds_read_b128 v[38:41], v17 offset:416
	ds_read_b128 v[92:95], v17 offset:432
	s_waitcnt lgkmcnt(0)
	v_pk_fma_f32 v[22:23], v[26:27], v[82:83], 0 op_sel_hi:[0,1,0]
	s_waitcnt lgkmcnt(2)
	v_pk_fma_f32 v[76:77], v[30:31], v[64:65], 0 op_sel_hi:[0,1,0]
	s_waitcnt lgkmcnt(1)
	v_pk_fma_f32 v[22:23], v[38:39], v[56:57], v[22:23] op_sel_hi:[0,1,1]
	s_waitcnt lgkmcnt(0)
	v_pk_fma_f32 v[76:77], v[92:93], v[48:49], v[76:77] op_sel_hi:[0,1,1]
	v_pk_fma_f32 v[22:23], v[26:27], v[62:63], v[22:23] op_sel:[1,0,0]
	v_pk_fma_f32 v[26:27], v[30:31], v[50:51], v[76:77] op_sel:[1,0,0]
	v_pk_fma_f32 v[22:23], v[38:39], v[42:43], v[22:23] op_sel:[1,0,0]
	v_pk_fma_f32 v[26:27], v[92:93], v[34:35], v[26:27] op_sel:[1,0,0]
	v_pk_fma_f32 v[22:23], v[28:29], v[58:59], v[22:23] op_sel_hi:[0,1,1]
	v_pk_fma_f32 v[26:27], v[32:33], v[54:55], v[26:27] op_sel_hi:[0,1,1]
	v_pk_fma_f32 v[22:23], v[40:41], v[46:47], v[22:23] op_sel_hi:[0,1,1]
	v_pk_fma_f32 v[26:27], v[94:95], v[84:85], v[26:27] op_sel_hi:[0,1,1]
	v_pk_fma_f32 v[22:23], v[28:29], v[60:61], v[22:23] op_sel:[1,0,0]
	v_pk_fma_f32 v[26:27], v[32:33], v[52:53], v[26:27] op_sel:[1,0,0]
	v_pk_fma_f32 v[22:23], v[40:41], v[44:45], v[22:23] op_sel:[1,0,0]
	v_pk_fma_f32 v[26:27], v[94:95], v[36:37], v[26:27] op_sel:[1,0,0]
	v_pk_mul_f32 v[28:29], v[80:81], v[18:19] op_sel:[0,1] op_sel_hi:[1,0]
	v_pk_add_f32 v[22:23], v[22:23], v[26:27]
	v_pk_fma_f32 v[26:27], v[78:79], v[18:19], v[28:29] neg_lo:[0,0,1]
	s_nop 0
	v_pk_add_f32 v[18:19], v[26:27], v[22:23]
	s_nop 0
	v_cvt_pk_bf16_f32 v22, v18, s0
	ds_write_b16 v16, v22 offset:1632
	v_cvt_pk_bf16_f32 v22, v19, s0
	ds_write_b16 v16, v22 offset:1760
	ds_read_b128 v[26:29], v17 offset:448
	ds_read_b128 v[30:33], v17 offset:464
	ds_read_b128 v[38:41], v17 offset:480
	ds_read_b128 v[92:95], v17 offset:496
	s_waitcnt lgkmcnt(0)
	v_pk_fma_f32 v[22:23], v[26:27], v[82:83], 0 op_sel_hi:[0,1,0]
	s_waitcnt lgkmcnt(2)
	v_pk_fma_f32 v[76:77], v[30:31], v[64:65], 0 op_sel_hi:[0,1,0]
	s_waitcnt lgkmcnt(1)
	v_pk_fma_f32 v[22:23], v[38:39], v[56:57], v[22:23] op_sel_hi:[0,1,1]
	s_waitcnt lgkmcnt(0)
	v_pk_fma_f32 v[76:77], v[92:93], v[48:49], v[76:77] op_sel_hi:[0,1,1]
	v_pk_fma_f32 v[22:23], v[26:27], v[62:63], v[22:23] op_sel:[1,0,0]
	v_pk_fma_f32 v[26:27], v[30:31], v[50:51], v[76:77] op_sel:[1,0,0]
	v_pk_fma_f32 v[22:23], v[38:39], v[42:43], v[22:23] op_sel:[1,0,0]
	v_pk_fma_f32 v[26:27], v[92:93], v[34:35], v[26:27] op_sel:[1,0,0]
	v_pk_fma_f32 v[22:23], v[28:29], v[58:59], v[22:23] op_sel_hi:[0,1,1]
	v_pk_fma_f32 v[26:27], v[32:33], v[54:55], v[26:27] op_sel_hi:[0,1,1]
	v_pk_fma_f32 v[22:23], v[40:41], v[46:47], v[22:23] op_sel_hi:[0,1,1]
	v_pk_fma_f32 v[26:27], v[94:95], v[84:85], v[26:27] op_sel_hi:[0,1,1]
	v_pk_fma_f32 v[22:23], v[28:29], v[60:61], v[22:23] op_sel:[1,0,0]
	v_pk_fma_f32 v[26:27], v[32:33], v[52:53], v[26:27] op_sel:[1,0,0]
	v_pk_fma_f32 v[22:23], v[40:41], v[44:45], v[22:23] op_sel:[1,0,0]
	v_pk_fma_f32 v[26:27], v[94:95], v[36:37], v[26:27] op_sel:[1,0,0]
	v_pk_mul_f32 v[28:29], v[80:81], v[18:19] op_sel:[0,1] op_sel_hi:[1,0]
	v_pk_add_f32 v[22:23], v[22:23], v[26:27]
	v_pk_fma_f32 v[26:27], v[78:79], v[18:19], v[28:29] neg_lo:[0,0,1]
	s_nop 0
	v_pk_add_f32 v[76:77], v[26:27], v[22:23]
	s_nop 0
	v_cvt_pk_bf16_f32 v17, v76, s0
	ds_write_b16 v16, v17 offset:1904
	v_cvt_pk_bf16_f32 v17, v77, s0
	ds_write_b16 v16, v17 offset:2032
	v_add_u32_e32 v16, 0x880, v16
	s_cbranch_scc0 .LBB0_208
	ds_read_b128 v[16:19], v90
	ds_read_b128 v[26:29], v90 offset:64
	v_lshl_or_b32 v25, s6, 4, v87
	v_or_b32_e32 v22, s8, v25
	v_mov_b32_e32 v23, s9
	s_add_i32 s6, s6, 1
	s_addk_i32 s10, 0x400
	s_cmp_eq_u32 s6, 4
	s_waitcnt lgkmcnt(0)
	v_mfma_f32_16x16x32_bf16 v[16:19], v[16:19], v[0:3], 0
	s_waitcnt lgkmcnt(0)
	v_mfma_f32_16x16x32_bf16 v[16:19], v[26:29], v[4:7], v[16:19]
	ds_read_b128 v[26:29], v90 offset:128
	s_waitcnt lgkmcnt(0)
	v_mfma_f32_16x16x32_bf16 v[16:19], v[26:29], v[8:11], v[16:19]
	ds_read_b128 v[26:29], v90 offset:192
	s_waitcnt lgkmcnt(0)
	v_mfma_f32_16x16x32_bf16 v[16:19], v[26:29], v[12:15], v[16:19]
	v_lshl_add_u32 v26, v25, 6, v88
	ds_read_b32 v26, v26 offset:34816
	s_waitcnt lgkmcnt(0)
	s_nop 4
	v_fma_f32 v16, v24, v26, v16
	v_mul_f32_e32 v26, 0x3d372713, v16
	v_mul_f32_e32 v26, v16, v26
	v_fma_f32 v26, v16, v26, v16
	v_mul_f32_e32 v26, 0x3f4c422a, v26
	v_mul_f32_e32 v26, -2.0, v26
	v_mul_f32_e32 v26, 0x3fb8aa3b, v26
	v_exp_f32_e32 v26, v26
	s_nop 0
	v_add_f32_e32 v26, 1.0, v26
	v_rcp_f32_e32 v26, v26
	s_nop 0
	v_mul_f32_e32 v16, v16, v26
	v_lshlrev_b64 v[26:27], 10, v[22:23]
	v_cvt_pk_bf16_f32 v16, v16, s0
	v_lshl_add_u64 v[26:27], v[20:21], 0, v[26:27]
	flat_store_short v[26:27], v16
	v_or_b32_e32 v16, 1, v25
	v_or_b32_e32 v22, s8, v16
	v_lshl_add_u32 v16, v16, 6, v88
	ds_read_b32 v16, v16 offset:34816
	s_waitcnt lgkmcnt(0)
	v_fma_f32 v16, v24, v16, v17
	v_mul_f32_e32 v17, 0x3d372713, v16
	v_mul_f32_e32 v17, v16, v17
	v_fma_f32 v17, v16, v17, v16
	v_mul_f32_e32 v17, 0x3f4c422a, v17
	v_mul_f32_e32 v17, -2.0, v17
	v_mul_f32_e32 v17, 0x3fb8aa3b, v17
	v_exp_f32_e32 v17, v17
	s_nop 0
	v_add_f32_e32 v17, 1.0, v17
	v_rcp_f32_e32 v17, v17
	s_nop 0
	v_mul_f32_e32 v16, v16, v17
	v_cvt_pk_bf16_f32 v26, v16, s0
	v_lshlrev_b64 v[16:17], 10, v[22:23]
	v_lshl_add_u64 v[16:17], v[20:21], 0, v[16:17]
	flat_store_short v[16:17], v26
	v_or_b32_e32 v16, 2, v25
	v_or_b32_e32 v22, s8, v16
	v_lshl_add_u32 v16, v16, 6, v88
	ds_read_b32 v16, v16 offset:34816
	s_waitcnt lgkmcnt(0)
	v_fma_f32 v16, v24, v16, v18
	v_mul_f32_e32 v17, 0x3d372713, v16
	v_mul_f32_e32 v17, v16, v17
	v_fma_f32 v17, v16, v17, v16
	v_mul_f32_e32 v17, 0x3f4c422a, v17
	v_mul_f32_e32 v17, -2.0, v17
	v_mul_f32_e32 v17, 0x3fb8aa3b, v17
	v_exp_f32_e32 v17, v17
	s_nop 0
	v_add_f32_e32 v17, 1.0, v17
	v_rcp_f32_e32 v17, v17
	s_nop 0
	v_mul_f32_e32 v16, v16, v17
	v_cvt_pk_bf16_f32 v18, v16, s0
	v_lshlrev_b64 v[16:17], 10, v[22:23]
	v_lshl_add_u64 v[16:17], v[20:21], 0, v[16:17]
	flat_store_short v[16:17], v18
	v_or_b32_e32 v16, 3, v25
	v_or_b32_e32 v22, s8, v16
	v_lshl_add_u32 v16, v16, 6, v88
	ds_read_b32 v16, v16 offset:34816
	s_waitcnt lgkmcnt(0)
	v_fmac_f32_e32 v19, v24, v16
	v_mul_f32_e32 v16, 0x3d372713, v19
	v_mul_f32_e32 v16, v19, v16
	v_fma_f32 v16, v19, v16, v19
	v_mul_f32_e32 v16, 0x3f4c422a, v16
	v_mul_f32_e32 v16, -2.0, v16
	v_mul_f32_e32 v16, 0x3fb8aa3b, v16
	v_exp_f32_e32 v16, v16
	s_nop 0
	v_add_f32_e32 v16, 1.0, v16
	v_rcp_f32_e32 v16, v16
	s_nop 0
	v_mul_f32_e32 v16, v19, v16
	v_cvt_pk_bf16_f32 v18, v16, s0
	v_lshlrev_b64 v[16:17], 10, v[22:23]
	v_lshl_add_u64 v[16:17], v[20:21], 0, v[16:17]
	flat_store_short v[16:17], v18
	s_cbranch_scc0 .LBB0_207
	s_mov_b32 s12, 0
	s_mov_b32 s6, s23
	s_branch .LBB0_162

.LBB0_233:
	s_add_i32 s6, s13, s1
	v_mov_b32_e32 v51, s6
	ds_read_b128 v[0:3], v51
	ds_read_b128 v[4:7], v51 offset:16
	ds_read_b128 v[52:55], v51 offset:32
	ds_read_b128 v[56:59], v51 offset:48
	s_addk_i32 s1, 0x200
	s_waitcnt lgkmcnt(3)
	v_pk_fma_f32 v[60:61], v[0:1], v[18:19], 0 op_sel_hi:[0,1,0]
	s_waitcnt lgkmcnt(2)
	v_pk_fma_f32 v[62:63], v[4:5], v[26:27], 0 op_sel_hi:[0,1,0]
	s_waitcnt lgkmcnt(1)
	v_pk_fma_f32 v[60:61], v[52:53], v[34:35], v[60:61] op_sel_hi:[0,1,1]
	s_waitcnt lgkmcnt(0)
	v_pk_fma_f32 v[62:63], v[56:57], v[42:43], v[62:63] op_sel_hi:[0,1,1]
	v_pk_fma_f32 v[0:1], v[0:1], v[20:21], v[60:61] op_sel:[1,0,0]
	v_pk_fma_f32 v[4:5], v[4:5], v[28:29], v[62:63] op_sel:[1,0,0]
	v_pk_fma_f32 v[0:1], v[52:53], v[36:37], v[0:1] op_sel:[1,0,0]
	v_pk_fma_f32 v[4:5], v[56:57], v[44:45], v[4:5] op_sel:[1,0,0]
	v_pk_fma_f32 v[0:1], v[2:3], v[22:23], v[0:1] op_sel_hi:[0,1,1]
	v_pk_fma_f32 v[4:5], v[6:7], v[30:31], v[4:5] op_sel_hi:[0,1,1]
	v_pk_fma_f32 v[0:1], v[54:55], v[38:39], v[0:1] op_sel_hi:[0,1,1]
	v_pk_fma_f32 v[4:5], v[58:59], v[46:47], v[4:5] op_sel_hi:[0,1,1]
	v_pk_fma_f32 v[0:1], v[2:3], v[24:25], v[0:1] op_sel:[1,0,0]
	v_mov_b32_e32 v2, v7
	v_pk_fma_f32 v[2:3], v[2:3], v[32:33], v[4:5] op_sel_hi:[0,1,1]
	v_pk_fma_f32 v[0:1], v[54:55], v[40:41], v[0:1] op_sel:[1,0,0]
	v_pk_fma_f32 v[2:3], v[58:59], v[48:49], v[2:3] op_sel:[1,0,0]
	v_pk_mul_f32 v[4:5], v[14:15], v[16:17] op_sel:[0,1] op_sel_hi:[1,0]
	v_pk_add_f32 v[0:1], v[2:3], v[0:1]
	v_pk_fma_f32 v[2:3], v[12:13], v[16:17], v[4:5] neg_lo:[0,0,1]
	s_cmpk_eq_i32 s1, 0x1000
	v_pk_add_f32 v[16:17], v[2:3], v[0:1]
	ds_read_b128 v[0:3], v51 offset:64
	ds_read_b128 v[4:7], v51 offset:80
	ds_read_b128 v[52:55], v51 offset:96
	ds_read_b128 v[56:59], v51 offset:112
	s_waitcnt lgkmcnt(3)
	v_pk_fma_f32 v[60:61], v[0:1], v[18:19], 0 op_sel_hi:[0,1,0]
	s_waitcnt lgkmcnt(2)
	v_pk_fma_f32 v[62:63], v[4:5], v[26:27], 0 op_sel_hi:[0,1,0]
	s_waitcnt lgkmcnt(1)
	v_pk_fma_f32 v[60:61], v[52:53], v[34:35], v[60:61] op_sel_hi:[0,1,1]
	s_waitcnt lgkmcnt(0)
	v_pk_fma_f32 v[62:63], v[56:57], v[42:43], v[62:63] op_sel_hi:[0,1,1]
	v_pk_fma_f32 v[0:1], v[0:1], v[20:21], v[60:61] op_sel:[1,0,0]
	v_pk_fma_f32 v[4:5], v[4:5], v[28:29], v[62:63] op_sel:[1,0,0]
	v_pk_fma_f32 v[0:1], v[52:53], v[36:37], v[0:1] op_sel:[1,0,0]
	v_pk_fma_f32 v[4:5], v[56:57], v[44:45], v[4:5] op_sel:[1,0,0]
	v_pk_fma_f32 v[0:1], v[2:3], v[22:23], v[0:1] op_sel_hi:[0,1,1]
	v_pk_fma_f32 v[4:5], v[6:7], v[30:31], v[4:5] op_sel_hi:[0,1,1]
	v_pk_fma_f32 v[0:1], v[54:55], v[38:39], v[0:1] op_sel_hi:[0,1,1]
	v_pk_fma_f32 v[4:5], v[58:59], v[46:47], v[4:5] op_sel_hi:[0,1,1]
	v_pk_fma_f32 v[0:1], v[2:3], v[24:25], v[0:1] op_sel:[1,0,0]
	v_mov_b32_e32 v2, v7
	v_pk_fma_f32 v[2:3], v[2:3], v[32:33], v[4:5] op_sel_hi:[0,1,1]
	v_pk_fma_f32 v[0:1], v[54:55], v[40:41], v[0:1] op_sel:[1,0,0]
	v_pk_fma_f32 v[2:3], v[58:59], v[48:49], v[2:3] op_sel:[1,0,0]
	v_pk_mul_f32 v[4:5], v[14:15], v[16:17] op_sel:[0,1] op_sel_hi:[1,0]
	v_pk_add_f32 v[0:1], v[2:3], v[0:1]
	v_pk_fma_f32 v[2:3], v[12:13], v[16:17], v[4:5] neg_lo:[0,0,1]
	s_nop 0
	v_pk_add_f32 v[16:17], v[2:3], v[0:1]
	ds_read_b128 v[0:3], v51 offset:128
	ds_read_b128 v[4:7], v51 offset:144
	ds_read_b128 v[52:55], v51 offset:160
	ds_read_b128 v[56:59], v51 offset:176
	s_waitcnt lgkmcnt(3)
	v_pk_fma_f32 v[60:61], v[0:1], v[18:19], 0 op_sel_hi:[0,1,0]
	s_waitcnt lgkmcnt(2)
	v_pk_fma_f32 v[62:63], v[4:5], v[26:27], 0 op_sel_hi:[0,1,0]
	s_waitcnt lgkmcnt(1)
	v_pk_fma_f32 v[60:61], v[52:53], v[34:35], v[60:61] op_sel_hi:[0,1,1]
	s_waitcnt lgkmcnt(0)
	v_pk_fma_f32 v[62:63], v[56:57], v[42:43], v[62:63] op_sel_hi:[0,1,1]
	v_pk_fma_f32 v[0:1], v[0:1], v[20:21], v[60:61] op_sel:[1,0,0]
	v_pk_fma_f32 v[4:5], v[4:5], v[28:29], v[62:63] op_sel:[1,0,0]
	v_pk_fma_f32 v[0:1], v[52:53], v[36:37], v[0:1] op_sel:[1,0,0]
	v_pk_fma_f32 v[4:5], v[56:57], v[44:45], v[4:5] op_sel:[1,0,0]
	v_pk_fma_f32 v[0:1], v[2:3], v[22:23], v[0:1] op_sel_hi:[0,1,1]
	v_pk_fma_f32 v[4:5], v[6:7], v[30:31], v[4:5] op_sel_hi:[0,1,1]
	v_pk_fma_f32 v[0:1], v[54:55], v[38:39], v[0:1] op_sel_hi:[0,1,1]
	v_pk_fma_f32 v[4:5], v[58:59], v[46:47], v[4:5] op_sel_hi:[0,1,1]
	v_pk_fma_f32 v[0:1], v[2:3], v[24:25], v[0:1] op_sel:[1,0,0]
	v_mov_b32_e32 v2, v7
	v_pk_fma_f32 v[2:3], v[2:3], v[32:33], v[4:5] op_sel_hi:[0,1,1]
	v_pk_fma_f32 v[0:1], v[54:55], v[40:41], v[0:1] op_sel:[1,0,0]
	v_pk_fma_f32 v[2:3], v[58:59], v[48:49], v[2:3] op_sel:[1,0,0]
	v_pk_mul_f32 v[4:5], v[14:15], v[16:17] op_sel:[0,1] op_sel_hi:[1,0]
	v_pk_add_f32 v[0:1], v[2:3], v[0:1]
	v_pk_fma_f32 v[2:3], v[12:13], v[16:17], v[4:5] neg_lo:[0,0,1]
	s_nop 0
	v_pk_add_f32 v[16:17], v[2:3], v[0:1]
	ds_read_b128 v[0:3], v51 offset:192
	ds_read_b128 v[4:7], v51 offset:208
	ds_read_b128 v[52:55], v51 offset:224
	ds_read_b128 v[56:59], v51 offset:240
	s_waitcnt lgkmcnt(3)
	v_pk_fma_f32 v[60:61], v[0:1], v[18:19], 0 op_sel_hi:[0,1,0]
	s_waitcnt lgkmcnt(2)
	v_pk_fma_f32 v[62:63], v[4:5], v[26:27], 0 op_sel_hi:[0,1,0]
	s_waitcnt lgkmcnt(1)
	v_pk_fma_f32 v[60:61], v[52:53], v[34:35], v[60:61] op_sel_hi:[0,1,1]
	s_waitcnt lgkmcnt(0)
	v_pk_fma_f32 v[62:63], v[56:57], v[42:43], v[62:63] op_sel_hi:[0,1,1]
	v_pk_fma_f32 v[0:1], v[0:1], v[20:21], v[60:61] op_sel:[1,0,0]
	v_pk_fma_f32 v[4:5], v[4:5], v[28:29], v[62:63] op_sel:[1,0,0]
	v_pk_fma_f32 v[0:1], v[52:53], v[36:37], v[0:1] op_sel:[1,0,0]
	v_pk_fma_f32 v[4:5], v[56:57], v[44:45], v[4:5] op_sel:[1,0,0]
	v_pk_fma_f32 v[0:1], v[2:3], v[22:23], v[0:1] op_sel_hi:[0,1,1]
	v_pk_fma_f32 v[4:5], v[6:7], v[30:31], v[4:5] op_sel_hi:[0,1,1]
	v_pk_fma_f32 v[0:1], v[54:55], v[38:39], v[0:1] op_sel_hi:[0,1,1]
	v_pk_fma_f32 v[4:5], v[58:59], v[46:47], v[4:5] op_sel_hi:[0,1,1]
	v_pk_fma_f32 v[0:1], v[2:3], v[24:25], v[0:1] op_sel:[1,0,0]
	v_mov_b32_e32 v2, v7
	v_pk_fma_f32 v[2:3], v[2:3], v[32:33], v[4:5] op_sel_hi:[0,1,1]
	v_pk_fma_f32 v[0:1], v[54:55], v[40:41], v[0:1] op_sel:[1,0,0]
	v_pk_fma_f32 v[2:3], v[58:59], v[48:49], v[2:3] op_sel:[1,0,0]
	v_pk_mul_f32 v[4:5], v[14:15], v[16:17] op_sel:[0,1] op_sel_hi:[1,0]
	v_pk_add_f32 v[0:1], v[2:3], v[0:1]
	v_pk_fma_f32 v[2:3], v[12:13], v[16:17], v[4:5] neg_lo:[0,0,1]
	s_nop 0
	v_pk_add_f32 v[16:17], v[2:3], v[0:1]
	ds_read_b128 v[0:3], v51 offset:256
	ds_read_b128 v[4:7], v51 offset:272
	ds_read_b128 v[52:55], v51 offset:288
	ds_read_b128 v[56:59], v51 offset:304
	s_waitcnt lgkmcnt(3)
	v_pk_fma_f32 v[60:61], v[0:1], v[18:19], 0 op_sel_hi:[0,1,0]
	s_waitcnt lgkmcnt(2)
	v_pk_fma_f32 v[62:63], v[4:5], v[26:27], 0 op_sel_hi:[0,1,0]
	s_waitcnt lgkmcnt(1)
	v_pk_fma_f32 v[60:61], v[52:53], v[34:35], v[60:61] op_sel_hi:[0,1,1]
	s_waitcnt lgkmcnt(0)
	v_pk_fma_f32 v[62:63], v[56:57], v[42:43], v[62:63] op_sel_hi:[0,1,1]
	v_pk_fma_f32 v[0:1], v[0:1], v[20:21], v[60:61] op_sel:[1,0,0]
	v_pk_fma_f32 v[4:5], v[4:5], v[28:29], v[62:63] op_sel:[1,0,0]
	v_pk_fma_f32 v[0:1], v[52:53], v[36:37], v[0:1] op_sel:[1,0,0]
	v_pk_fma_f32 v[4:5], v[56:57], v[44:45], v[4:5] op_sel:[1,0,0]
	v_pk_fma_f32 v[0:1], v[2:3], v[22:23], v[0:1] op_sel_hi:[0,1,1]
	v_pk_fma_f32 v[4:5], v[6:7], v[30:31], v[4:5] op_sel_hi:[0,1,1]
	v_pk_fma_f32 v[0:1], v[54:55], v[38:39], v[0:1] op_sel_hi:[0,1,1]
	v_pk_fma_f32 v[4:5], v[58:59], v[46:47], v[4:5] op_sel_hi:[0,1,1]
	v_pk_fma_f32 v[0:1], v[2:3], v[24:25], v[0:1] op_sel:[1,0,0]
	v_mov_b32_e32 v2, v7
	v_pk_fma_f32 v[2:3], v[2:3], v[32:33], v[4:5] op_sel_hi:[0,1,1]
	v_pk_fma_f32 v[0:1], v[54:55], v[40:41], v[0:1] op_sel:[1,0,0]
	v_pk_fma_f32 v[2:3], v[58:59], v[48:49], v[2:3] op_sel:[1,0,0]
	v_pk_mul_f32 v[4:5], v[14:15], v[16:17] op_sel:[0,1] op_sel_hi:[1,0]
	v_pk_add_f32 v[0:1], v[2:3], v[0:1]
	v_pk_fma_f32 v[2:3], v[12:13], v[16:17], v[4:5] neg_lo:[0,0,1]
	s_nop 0
	v_pk_add_f32 v[16:17], v[2:3], v[0:1]
	ds_read_b128 v[0:3], v51 offset:320
	ds_read_b128 v[4:7], v51 offset:336
	ds_read_b128 v[52:55], v51 offset:352
	ds_read_b128 v[56:59], v51 offset:368
	s_waitcnt lgkmcnt(3)
	v_pk_fma_f32 v[60:61], v[0:1], v[18:19], 0 op_sel_hi:[0,1,0]
	s_waitcnt lgkmcnt(2)
	v_pk_fma_f32 v[62:63], v[4:5], v[26:27], 0 op_sel_hi:[0,1,0]
	s_waitcnt lgkmcnt(1)
	v_pk_fma_f32 v[60:61], v[52:53], v[34:35], v[60:61] op_sel_hi:[0,1,1]
	s_waitcnt lgkmcnt(0)
	v_pk_fma_f32 v[62:63], v[56:57], v[42:43], v[62:63] op_sel_hi:[0,1,1]
	v_pk_fma_f32 v[0:1], v[0:1], v[20:21], v[60:61] op_sel:[1,0,0]
	v_pk_fma_f32 v[4:5], v[4:5], v[28:29], v[62:63] op_sel:[1,0,0]
	v_pk_fma_f32 v[0:1], v[52:53], v[36:37], v[0:1] op_sel:[1,0,0]
	v_pk_fma_f32 v[4:5], v[56:57], v[44:45], v[4:5] op_sel:[1,0,0]
	v_pk_fma_f32 v[0:1], v[2:3], v[22:23], v[0:1] op_sel_hi:[0,1,1]
	v_pk_fma_f32 v[4:5], v[6:7], v[30:31], v[4:5] op_sel_hi:[0,1,1]
	v_pk_fma_f32 v[0:1], v[54:55], v[38:39], v[0:1] op_sel_hi:[0,1,1]
	v_pk_fma_f32 v[4:5], v[58:59], v[46:47], v[4:5] op_sel_hi:[0,1,1]
	v_pk_fma_f32 v[0:1], v[2:3], v[24:25], v[0:1] op_sel:[1,0,0]
	v_mov_b32_e32 v2, v7
	v_pk_fma_f32 v[2:3], v[2:3], v[32:33], v[4:5] op_sel_hi:[0,1,1]
	v_pk_fma_f32 v[0:1], v[54:55], v[40:41], v[0:1] op_sel:[1,0,0]
	v_pk_fma_f32 v[2:3], v[58:59], v[48:49], v[2:3] op_sel:[1,0,0]
	v_pk_mul_f32 v[4:5], v[14:15], v[16:17] op_sel:[0,1] op_sel_hi:[1,0]
	v_pk_add_f32 v[0:1], v[2:3], v[0:1]
	v_pk_fma_f32 v[2:3], v[12:13], v[16:17], v[4:5] neg_lo:[0,0,1]
	s_nop 0
	v_pk_add_f32 v[16:17], v[2:3], v[0:1]
	ds_read_b128 v[0:3], v51 offset:384
	ds_read_b128 v[4:7], v51 offset:400
	ds_read_b128 v[52:55], v51 offset:416
	ds_read_b128 v[56:59], v51 offset:432
	s_waitcnt lgkmcnt(3)
	v_pk_fma_f32 v[60:61], v[0:1], v[18:19], 0 op_sel_hi:[0,1,0]
	s_waitcnt lgkmcnt(2)
	v_pk_fma_f32 v[62:63], v[4:5], v[26:27], 0 op_sel_hi:[0,1,0]
	s_waitcnt lgkmcnt(1)
	v_pk_fma_f32 v[60:61], v[52:53], v[34:35], v[60:61] op_sel_hi:[0,1,1]
	s_waitcnt lgkmcnt(0)
	v_pk_fma_f32 v[62:63], v[56:57], v[42:43], v[62:63] op_sel_hi:[0,1,1]
	v_pk_fma_f32 v[0:1], v[0:1], v[20:21], v[60:61] op_sel:[1,0,0]
	v_pk_fma_f32 v[4:5], v[4:5], v[28:29], v[62:63] op_sel:[1,0,0]
	v_pk_fma_f32 v[0:1], v[52:53], v[36:37], v[0:1] op_sel:[1,0,0]
	v_pk_fma_f32 v[4:5], v[56:57], v[44:45], v[4:5] op_sel:[1,0,0]
	v_pk_fma_f32 v[0:1], v[2:3], v[22:23], v[0:1] op_sel_hi:[0,1,1]
	v_pk_fma_f32 v[4:5], v[6:7], v[30:31], v[4:5] op_sel_hi:[0,1,1]
	v_pk_fma_f32 v[0:1], v[54:55], v[38:39], v[0:1] op_sel_hi:[0,1,1]
	v_pk_fma_f32 v[4:5], v[58:59], v[46:47], v[4:5] op_sel_hi:[0,1,1]
	v_pk_fma_f32 v[0:1], v[2:3], v[24:25], v[0:1] op_sel:[1,0,0]
	v_mov_b32_e32 v2, v7
	v_pk_fma_f32 v[2:3], v[2:3], v[32:33], v[4:5] op_sel_hi:[0,1,1]
	v_pk_fma_f32 v[0:1], v[54:55], v[40:41], v[0:1] op_sel:[1,0,0]
	v_pk_fma_f32 v[2:3], v[58:59], v[48:49], v[2:3] op_sel:[1,0,0]
	v_pk_mul_f32 v[4:5], v[14:15], v[16:17] op_sel:[0,1] op_sel_hi:[1,0]
	v_pk_add_f32 v[0:1], v[2:3], v[0:1]
	v_pk_fma_f32 v[2:3], v[12:13], v[16:17], v[4:5] neg_lo:[0,0,1]
	s_nop 0
	v_pk_add_f32 v[16:17], v[2:3], v[0:1]
	ds_read_b128 v[0:3], v51 offset:448
	ds_read_b128 v[4:7], v51 offset:464
	ds_read_b128 v[52:55], v51 offset:480
	ds_read_b128 v[56:59], v51 offset:496
	s_waitcnt lgkmcnt(3)
	v_pk_fma_f32 v[60:61], v[0:1], v[18:19], 0 op_sel_hi:[0,1,0]
	s_waitcnt lgkmcnt(2)
	v_pk_fma_f32 v[62:63], v[4:5], v[26:27], 0 op_sel_hi:[0,1,0]
	s_waitcnt lgkmcnt(1)
	v_pk_fma_f32 v[60:61], v[52:53], v[34:35], v[60:61] op_sel_hi:[0,1,1]
	s_waitcnt lgkmcnt(0)
	v_pk_fma_f32 v[62:63], v[56:57], v[42:43], v[62:63] op_sel_hi:[0,1,1]
	v_pk_fma_f32 v[0:1], v[0:1], v[20:21], v[60:61] op_sel:[1,0,0]
	v_pk_fma_f32 v[4:5], v[4:5], v[28:29], v[62:63] op_sel:[1,0,0]
	v_pk_fma_f32 v[0:1], v[52:53], v[36:37], v[0:1] op_sel:[1,0,0]
	v_pk_fma_f32 v[4:5], v[56:57], v[44:45], v[4:5] op_sel:[1,0,0]
	v_pk_fma_f32 v[0:1], v[2:3], v[22:23], v[0:1] op_sel_hi:[0,1,1]
	v_pk_fma_f32 v[4:5], v[6:7], v[30:31], v[4:5] op_sel_hi:[0,1,1]
	v_pk_fma_f32 v[0:1], v[54:55], v[38:39], v[0:1] op_sel_hi:[0,1,1]
	v_pk_fma_f32 v[4:5], v[58:59], v[46:47], v[4:5] op_sel_hi:[0,1,1]
	v_pk_fma_f32 v[0:1], v[2:3], v[24:25], v[0:1] op_sel:[1,0,0]
	v_mov_b32_e32 v2, v7
	v_pk_fma_f32 v[2:3], v[2:3], v[32:33], v[4:5] op_sel_hi:[0,1,1]
	v_pk_fma_f32 v[0:1], v[54:55], v[40:41], v[0:1] op_sel:[1,0,0]
	v_pk_fma_f32 v[2:3], v[58:59], v[48:49], v[2:3] op_sel:[1,0,0]
	v_pk_mul_f32 v[4:5], v[14:15], v[16:17] op_sel:[0,1] op_sel_hi:[1,0]
	v_pk_add_f32 v[0:1], v[2:3], v[0:1]
	v_pk_fma_f32 v[2:3], v[12:13], v[16:17], v[4:5] neg_lo:[0,0,1]
	s_nop 0
	v_pk_add_f32 v[16:17], v[2:3], v[0:1]
	s_cbranch_scc0 .LBB0_233
	s_ashr_i32 s1, s0, 31
	s_lshl_b64 s[8:9], s[0:1], 9
	s_add_i32 s0, s0, s36
	v_lshl_add_u64 v[0:1], v[8:9], 0, s[8:9]
	s_cmpk_gt_i32 s0, 0x1fff
	flat_store_dwordx2 v[0:1], v[16:17]
	s_cbranch_scc0 .LBB0_222
